# P4: odd workgroups start 12 us late so the in-projection epilogue store bursts of the two halves of the chip do not coincide
# baseline (speedup 1.0000x reference)
.LBB0_374:
.LBB0_375:
	s_cmp_lt_i32 s14, 5
	s_cselect_b64 s[0:1], -1, 0
	s_cmp_gt_i32 s15, 4
	s_cselect_b64 s[4:5], -1, 0
	s_and_b64 s[0:1], s[0:1], s[4:5]
	s_andn2_b64 vcc, exec, s[0:1]
	s_cbranch_vccnz .LBB0_1142
	s_and_b32 s62, s2, 1
	s_cmp_eq_u32 s62, 0
	s_cbranch_scc1 .Lp4_nodelay
	s_mul_i32 s63, s62, 1200
	s_memrealtime s[64:65]
	s_waitcnt lgkmcnt(0)
	s_mov_b32 s62, s64
.Lp4_spin:
	s_sleep 2
	s_memrealtime s[64:65]
	s_waitcnt lgkmcnt(0)
	s_sub_u32 s64, s64, s62
	s_cmp_lt_u32 s64, s63
	s_cbranch_scc1 .Lp4_spin
.Lp4_nodelay:
	s_waitcnt vmcnt(0)
	v_mov_b32_e32 v10, v0
	s_cmpk_lt_i32 s2, 0x50a
	s_cselect_b64 s[0:1], -1, 0
	s_cmpk_gt_i32 s2, 0x509
	v_readfirstlane_b32 s6, v10
	s_cbranch_scc1 .LBB0_382
	s_ashr_i32 s3, s2, 31
	s_lshr_b32 s3, s3, 29
	s_add_i32 s3, s2, s3
	s_and_b32 s4, s3, -8
	s_sub_i32 s7, s2, s4
	s_cmp_gt_i32 s7, 1
	s_cbranch_scc0 .LBB0_379
	s_mul_i32 s4, s7, 0xa1
	s_add_i32 s8, s4, 2
	s_cbranch_execz .LBB0_380
	s_branch .LBB0_381
